# P4 output pass split 6/10 by workgroup group; attention units re-dealt 36/32 block pairs (four units per workgroup)
# speedup vs baseline: 1.0087x; 1.0087x over previous
;   __device__ __forceinline__ bool next(int i,AttnUnit&u)const{
;     if(G==256){ if(i>=4)return false; const int s=vcu&3; u.bh=vcu>>2; u.qb=(i==0)?s:(i==1)?7-s:(i==2)?8+s:15-s; return true; }
;     const int L=i*G+vcu; if(L>=BATCH*NHEAD*NQB)return false; u.bh=L/NQB; u.qb=NQB-1-(L%NQB); return true; }
.LBB0_549:
	s_andn2_b64 vcc, exec, s[6:7]
	s_cbranch_vccnz .LBB0_558
	s_bfe_u32 s3, s22, 0x10004
	s_and_b32 s10, s22, 3
	s_lshl_b32 s3, s3, 2
	s_or_b32 s3, s3, s10
	s_mov_b32 s10, 0x8a4aef
	s_cmp_eq_u32 s3, 1
	s_cselect_b32 s10, 0xca5abf, s10
	s_cmp_eq_u32 s3, 2
	s_cselect_b32 s10, 0x826b2e, s10
	s_cmp_eq_u32 s3, 3
	s_cselect_b32 s10, 0x874b7e, s10
	s_cmp_eq_u32 s3, 4
	s_cselect_b32 s10, 0x826a6d, s10
	s_cmp_eq_u32 s3, 5
	s_cselect_b32 s10, 0x867a2c, s10
	s_cmp_eq_u32 s3, 6
	s_cselect_b32 s10, 0x8e5e6b, s10
	s_cmp_eq_u32 s3, 7
	s_cselect_b32 s10, 0xcf7e2a, s10
	s_mul_i32 s3, s70, 6
	s_min_u32 s3, s3, 31
	s_lshr_b32 s10, s10, s3
	s_bitcmp1_b32 s10, 5
	s_cbranch_scc0 .Lau_done
	s_and_b32 s72, s10, 15
	s_lshr_b32 s3, s10, 2
	s_and_b32 s3, s3, 4
	s_xor_b32 s71, s60, s3
	s_mov_b64 s[4:5], -1
	s_branch .LBB0_559
